# counted lgkmcnt waits: QK^T MFMAs of the B selected/window loops and of mixer C wait only for the K fragments they multiply (V^T fragments stay in flight); mixer C exchange readers sunk behind the nex
# speedup vs baseline: 1.0046x; 1.0046x over previous
.Lcc_noload:
	s_cmp_gt_i32 s13, s12
	s_cbranch_scc1 .Lcc_after
	s_cmp_lg_u32 s15, 0
	s_cbranch_scc1 .Lcc_after
	v_add_u32_e32 v135, s14, v127
	ds_read_b128 v[100:103], v135 offset:16384
	ds_read_b128 v[68:71], v135 offset:16448
	ds_read_b128 v[96:99], v135 offset:18944
	ds_read_b128 v[64:67], v135 offset:19008
	ds_read_b128 v[92:95], v135 offset:21504
	ds_read_b128 v[60:63], v135 offset:21568
	ds_read_b128 v[84:87], v135 offset:24064
	ds_read_b128 v[56:59], v135 offset:24128
	ds_read_b128 v[52:55], v135 offset:26624
	ds_read_b128 v[48:51], v135 offset:26688
	ds_read_b128 v[44:47], v135 offset:29184
	ds_read_b128 v[40:43], v135 offset:29248
	ds_read_b128 v[36:39], v135 offset:31744
	ds_read_b128 v[32:35], v135 offset:31808
	ds_read_b128 v[28:31], v135 offset:34304
	ds_read_b128 v[24:27], v135 offset:34368
	s_lshl_b32 s19, s13, 6
	v_add_u32_e32 v91, s19, v116
	v_cmp_lt_i32_e32 vcc, v91, v72
	s_cmp_lg_u32 s13, 0
	s_waitcnt lgkmcnt(8)
	v_mfma_f32_16x16x32_bf16 v[84:87], v[84:87], v[16:19], 0
	v_mfma_f32_16x16x32_bf16 v[100:103], v[100:103], v[16:19], 0
	v_mfma_f32_16x16x32_bf16 v[68:71], v[68:71], v[20:23], v[100:103]
	v_mfma_f32_16x16x32_bf16 v[56:59], v[56:59], v[20:23], v[84:87]
	v_mfma_f32_16x16x32_bf16 v[92:95], v[92:95], v[16:19], 0
	s_nop 5
	v_mul_f32_e32 v82, 0x3e000000, v68
	v_mul_f32_e64 v84, |v82|, s80
	v_exp_f32_e32 v84, v84
	v_max_f32_e32 v82, 0, v82
	v_mfma_f32_16x16x32_bf16 v[60:63], v[60:63], v[20:23], v[92:95]
	v_add_f32_e32 v84, 1.0, v84
	v_log_f32_e32 v84, v84
	v_mfma_f32_16x16x32_bf16 v[96:99], v[96:99], v[16:19], 0
	v_fmac_f32_e32 v82, 0x3f317218, v84
	v_fma_f32 v68, v68, s70, -v82
	v_cndmask_b32_e32 v92, v241, v68, vcc
	v_sub_f32_e32 v68, 0, v82
	v_add_u32_e32 v82, 1, v91
	v_cndmask_b32_e32 v68, 0, v68, vcc
	v_cmp_lt_i32_e32 vcc, v82, v72
	v_mul_f32_e32 v82, 0x3e000000, v69
	v_mul_f32_e64 v84, |v82|, s80
	v_exp_f32_e32 v84, v84
	v_max_f32_e32 v82, 0, v82
	v_mfma_f32_16x16x32_bf16 v[64:67], v[64:67], v[20:23], v[96:99]
	v_add_f32_e32 v84, 1.0, v84
	v_log_f32_e32 v84, v84
	s_nop 0
	v_fmac_f32_e32 v82, 0x3f317218, v84
	v_fma_f32 v69, v69, s70, -v82
	v_cndmask_b32_e32 v98, v241, v69, vcc
	v_add_u32_e32 v69, 2, v91
	v_cndmask_b32_e64 v97, 0, -v82, vcc
	v_cmp_lt_i32_e32 vcc, v69, v72
	v_mul_f32_e32 v69, 0x3e000000, v70
	v_mul_f32_e64 v82, |v69|, s80
	v_exp_f32_e32 v82, v82
	v_max_f32_e32 v69, 0, v69
	v_add_f32_e32 v68, v97, v68
	v_add_f32_e32 v82, 1.0, v82
	v_log_f32_e32 v82, v82
	s_nop 0
	v_fmac_f32_e32 v69, 0x3f317218, v82
	v_cndmask_b32_e64 v99, 0, -v69, vcc
	v_fma_f32 v69, v70, s70, -v69
	v_cndmask_b32_e32 v100, v241, v69, vcc
	v_add_u32_e32 v69, 3, v91
	v_cmp_lt_i32_e32 vcc, v69, v72
	v_mul_f32_e32 v69, 0x3e000000, v71
	v_mul_f32_e64 v70, |v69|, s80
	v_exp_f32_e32 v70, v70
	v_max_f32_e32 v69, 0, v69
	v_add_f32_e32 v68, v99, v68
	v_add_f32_e32 v70, 1.0, v70
	v_log_f32_e32 v70, v70
	s_nop 0
	v_fmac_f32_e32 v69, 0x3f317218, v70
	v_cndmask_b32_e64 v101, 0, -v69, vcc
	v_fma_f32 v69, v71, s70, -v69
	v_cndmask_b32_e32 v102, v241, v69, vcc
	v_add_u32_e32 v69, 16, v91
	v_cmp_lt_i32_e32 vcc, v69, v72
	v_mul_f32_e32 v69, 0x3e000000, v64
	v_mul_f32_e64 v71, |v69|, s80
	v_exp_f32_e32 v71, v71
	v_max_f32_e32 v69, 0, v69
	v_add_f32_e32 v93, v101, v68
	ds_bpermute_b32 v94, v88, v93
	v_add_f32_e32 v71, 1.0, v71
	v_log_f32_e32 v71, v71
	ds_bpermute_b32 v95, v89, v93
	ds_bpermute_b32 v96, v90, v93
	v_fmac_f32_e32 v69, 0x3f317218, v71
	v_fma_f32 v64, v64, s70, -v69
	v_cndmask_b32_e32 v103, v241, v64, vcc
	v_sub_f32_e32 v64, 0, v69
	v_add_u32_e32 v69, 17, v91
	v_cndmask_b32_e32 v64, 0, v64, vcc
	v_cmp_lt_i32_e32 vcc, v69, v72
	v_mul_f32_e32 v69, 0x3e000000, v65
	v_mul_f32_e64 v71, |v69|, s80
	v_exp_f32_e32 v71, v71
	v_max_f32_e32 v69, 0, v69
	v_add_f32_e32 v71, 1.0, v71
	v_log_f32_e32 v71, v71
	s_nop 0
	v_fmac_f32_e32 v69, 0x3f317218, v71
	v_fma_f32 v65, v65, s70, -v69
	v_cndmask_b32_e32 v105, v241, v65, vcc
	v_add_u32_e32 v65, 18, v91
	v_cndmask_b32_e64 v104, 0, -v69, vcc
	v_cmp_lt_i32_e32 vcc, v65, v72
	v_mul_f32_e32 v65, 0x3e000000, v66
	v_mul_f32_e64 v69, |v65|, s80
	v_exp_f32_e32 v69, v69
	v_max_f32_e32 v65, 0, v65
	v_add_f32_e32 v64, v104, v64
	v_add_f32_e32 v69, 1.0, v69
	v_log_f32_e32 v69, v69
	s_nop 0
	v_fmac_f32_e32 v65, 0x3f317218, v69
	v_cndmask_b32_e64 v106, 0, -v65, vcc
	v_fma_f32 v65, v66, s70, -v65
	v_cndmask_b32_e32 v107, v241, v65, vcc
	v_add_u32_e32 v65, 19, v91
	v_cmp_lt_i32_e32 vcc, v65, v72
	v_mul_f32_e32 v65, 0x3e000000, v67
	v_mul_f32_e64 v66, |v65|, s80
	v_exp_f32_e32 v66, v66
	v_max_f32_e32 v65, 0, v65
	v_add_f32_e32 v64, v106, v64
	v_add_f32_e32 v66, 1.0, v66
	v_log_f32_e32 v66, v66
	s_nop 0
	v_fmac_f32_e32 v65, 0x3f317218, v66
	v_cndmask_b32_e64 v108, 0, -v65, vcc
	v_fma_f32 v65, v67, s70, -v65
	v_add_f32_e32 v64, v108, v64
	v_cndmask_b32_e32 v109, v241, v65, vcc
	s_waitcnt lgkmcnt(0)
	v_cndmask_b32_e64 v70, 0, v94, s[6:7]
	v_cndmask_b32_e64 v84, 0, v95, s[8:9]
	v_cndmask_b32_e64 v68, 0, v96, s[10:11]
	ds_bpermute_b32 v208, v88, v64
	ds_bpermute_b32 v209, v89, v64
	ds_bpermute_b32 v85, v90, v64
	v_add_u32_e32 v65, 32, v91
	v_cmp_lt_i32_e32 vcc, v65, v72
	v_mul_f32_e32 v65, 0x3e000000, v60
	v_mul_f32_e64 v67, |v65|, s80
	v_exp_f32_e32 v67, v67
	v_max_f32_e32 v65, 0, v65
	v_add_f32_e32 v67, 1.0, v67
	v_log_f32_e32 v67, v67
	s_nop 0
	v_fmac_f32_e32 v65, 0x3f317218, v67
	v_fma_f32 v60, v60, s70, -v65
	v_cndmask_b32_e32 v110, v241, v60, vcc
	v_sub_f32_e32 v60, 0, v65
	v_add_u32_e32 v65, 33, v91
	v_cndmask_b32_e32 v60, 0, v60, vcc
	v_cmp_lt_i32_e32 vcc, v65, v72
	v_mul_f32_e32 v65, 0x3e000000, v61
	v_mul_f32_e64 v67, |v65|, s80
	v_exp_f32_e32 v67, v67
	v_max_f32_e32 v65, 0, v65
	v_add_f32_e32 v67, 1.0, v67
	v_log_f32_e32 v67, v67
	s_nop 0
	v_fmac_f32_e32 v65, 0x3f317218, v67
	v_fma_f32 v61, v61, s70, -v65
	v_cndmask_b32_e32 v112, v241, v61, vcc
	v_add_u32_e32 v61, 34, v91
	v_cndmask_b32_e64 v111, 0, -v65, vcc
	v_cmp_lt_i32_e32 vcc, v61, v72
	v_mul_f32_e32 v61, 0x3e000000, v62
	v_mul_f32_e64 v65, |v61|, s80
	v_exp_f32_e32 v65, v65
	v_max_f32_e32 v61, 0, v61
	v_add_f32_e32 v60, v111, v60
	v_add_f32_e32 v65, 1.0, v65
	v_log_f32_e32 v65, v65
	s_nop 0
	v_fmac_f32_e32 v61, 0x3f317218, v65
	v_cndmask_b32_e64 v113, 0, -v61, vcc
	v_fma_f32 v61, v62, s70, -v61
	v_cndmask_b32_e32 v114, v241, v61, vcc
	v_add_u32_e32 v61, 35, v91
	v_cmp_lt_i32_e32 vcc, v61, v72
	v_mul_f32_e32 v61, 0x3e000000, v63
	v_mul_f32_e64 v62, |v61|, s80
	v_exp_f32_e32 v62, v62
	v_max_f32_e32 v61, 0, v61
	v_add_f32_e32 v60, v113, v60
	v_add_f32_e32 v62, 1.0, v62
	v_log_f32_e32 v62, v62
	s_nop 0
	v_fmac_f32_e32 v61, 0x3f317218, v62
	v_cndmask_b32_e64 v117, 0, -v61, vcc
	v_fma_f32 v61, v63, s70, -v61
	v_add_f32_e32 v60, v117, v60
	v_cndmask_b32_e32 v118, v241, v61, vcc
	s_waitcnt lgkmcnt(0)
	v_add_f32_e32 v64, v64, v208
	v_cndmask_b32_e64 v66, 0, v208, s[6:7]
	v_add_f32_e32 v71, v64, v209
	v_cndmask_b32_e64 v86, 0, v209, s[8:9]
	v_cndmask_b32_e64 v64, 0, v85, s[10:11]
	ds_bpermute_b32 v211, v88, v60
	ds_bpermute_b32 v212, v89, v60
	ds_bpermute_b32 v87, v90, v60
	v_add_u32_e32 v61, 48, v91
	v_cmp_lt_i32_e32 vcc, v61, v72
	v_mul_f32_e32 v61, 0x3e000000, v56
	v_mul_f32_e64 v63, |v61|, s80
	v_exp_f32_e32 v63, v63
	v_max_f32_e32 v61, 0, v61
	v_add_f32_e32 v63, 1.0, v63
	v_log_f32_e32 v63, v63
	s_nop 0
	v_fmac_f32_e32 v61, 0x3f317218, v63
	v_fma_f32 v56, v56, s70, -v61
	v_cndmask_b32_e32 v119, v241, v56, vcc
	v_sub_f32_e32 v56, 0, v61
	v_add_u32_e32 v61, 49, v91
	v_cndmask_b32_e32 v56, 0, v56, vcc
	v_cmp_lt_i32_e32 vcc, v61, v72
	v_mul_f32_e32 v61, 0x3e000000, v57
	v_mul_f32_e64 v63, |v61|, s80
	v_exp_f32_e32 v63, v63
	v_max_f32_e32 v61, 0, v61
	v_add_f32_e32 v63, 1.0, v63
	v_log_f32_e32 v63, v63
	s_nop 0
	v_fmac_f32_e32 v61, 0x3f317218, v63
	v_fma_f32 v57, v57, s70, -v61
	v_cndmask_b32_e32 v121, v241, v57, vcc
	v_add_u32_e32 v57, 50, v91
	v_cndmask_b32_e64 v120, 0, -v61, vcc
	v_cmp_lt_i32_e32 vcc, v57, v72
	v_mul_f32_e32 v57, 0x3e000000, v58
	v_mul_f32_e64 v61, |v57|, s80
	v_exp_f32_e32 v61, v61
	v_max_f32_e32 v57, 0, v57
	v_add_f32_e32 v56, v120, v56
	v_add_f32_e32 v61, 1.0, v61
	v_log_f32_e32 v61, v61
	s_nop 0
	v_fmac_f32_e32 v57, 0x3f317218, v61
	v_cndmask_b32_e64 v122, 0, -v57, vcc
	v_fma_f32 v57, v58, s70, -v57
	v_cndmask_b32_e32 v123, v241, v57, vcc
	v_add_u32_e32 v57, 51, v91
	v_cmp_lt_i32_e32 vcc, v57, v72
	v_mul_f32_e32 v57, 0x3e000000, v59
	v_mul_f32_e64 v58, |v57|, s80
	v_exp_f32_e32 v58, v58
	v_max_f32_e32 v57, 0, v57
	v_add_f32_e32 v56, v122, v56
	v_add_f32_e32 v58, 1.0, v58
	v_log_f32_e32 v58, v58
	s_nop 0
	v_fmac_f32_e32 v57, 0x3f317218, v58
	v_cndmask_b32_e64 v124, 0, -v57, vcc
	v_fma_f32 v57, v59, s70, -v57
	v_add_f32_e32 v56, v124, v56
	v_cndmask_b32_e32 v125, v241, v57, vcc
	s_waitcnt lgkmcnt(0)
	v_add_f32_e32 v60, v60, v211
	v_add_f32_e32 v67, v60, v212
	v_cndmask_b32_e64 v60, 0, v211, s[6:7]
	v_cndmask_b32_e64 v62, 0, v212, s[8:9]
	v_cndmask_b32_e64 v82, 0, v87, s[10:11]
	ds_bpermute_b32 v57, v88, v56
	ds_bpermute_b32 v58, v89, v56
	ds_bpermute_b32 v63, v90, v56
	s_waitcnt lgkmcnt(2)
	v_add_f32_e32 v56, v56, v57
	s_waitcnt lgkmcnt(1)
	v_add_f32_e32 v61, v56, v58
	v_cndmask_b32_e64 v56, 0, v57, s[6:7]
	v_cndmask_b32_e64 v57, 0, v58, s[8:9]
	v_add_f32_e32 v56, v56, v57
	s_waitcnt lgkmcnt(0)
	v_cndmask_b32_e64 v57, 0, v63, s[10:11]
	v_add_f32_e32 v56, v56, v57
	v_add_f32_e32 v126, v83, v56
	v_pk_add_f32 v[56:57], v[60:61], v[62:63]
	v_pk_add_f32 v[58:59], v[66:67], v[86:87]
	v_pk_add_f32 v[60:61], v[56:57], v[82:83]
	v_add_f32_e32 v82, v124, v126
	v_mov_b32_e32 v65, v61
	v_pk_add_f32 v[62:63], v[58:59], v[64:65]
	v_add_f32_e32 v56, v60, v61
	v_pk_add_f32 v[60:61], v[70:71], v[84:85]
	v_mov_b32_e32 v69, v63
	v_add_f32_e32 v58, v62, v63
	v_pk_add_f32 v[62:63], v[60:61], v[68:69]
	v_add_f32_e32 v65, v109, v58
	v_add_f32_e32 v60, v62, v63
	v_add_f32_e32 v62, v102, v60
	v_mul_f32_e32 v62, 0x3fb8aa3b, v62
	v_add_f32_e32 v60, v101, v60
	v_exp_f32_e32 v63, v62
	v_add_f32_e32 v62, v100, v60
	v_add_f32_e32 v58, v108, v58
	v_mul_f32_e32 v62, 0x3fb8aa3b, v62
	v_add_f32_e32 v60, v99, v60
	v_add_f32_e32 v66, v107, v58
	v_add_f32_e32 v58, v106, v58
	v_exp_f32_e32 v64, v62
	v_add_f32_e32 v62, v98, v60
	v_add_f32_e32 v60, v97, v60
	v_add_f32_e32 v67, v105, v58
	v_add_f32_e32 v58, v104, v58
	v_add_f32_e32 v60, v92, v60
	v_add_f32_e32 v58, v103, v58
	v_mul_f32_e32 v62, 0x3fb8aa3b, v62
	v_mul_f32_e32 v60, 0x3fb8aa3b, v60
	v_mul_f32_e32 v65, 0x3fb8aa3b, v65
	v_mul_f32_e32 v66, 0x3fb8aa3b, v66
	v_mul_f32_e32 v67, 0x3fb8aa3b, v67
	v_mul_f32_e32 v58, 0x3fb8aa3b, v58
	v_add_f32_e32 v68, v118, v56
	v_add_f32_e32 v56, v117, v56
	v_exp_f32_e32 v62, v62
	v_exp_f32_e32 v60, v60
	v_exp_f32_e32 v65, v65
	v_exp_f32_e32 v66, v66
	v_exp_f32_e32 v67, v67
	v_exp_f32_e32 v58, v58
	v_add_f32_e32 v69, v114, v56
	v_add_f32_e32 v56, v113, v56
	v_add_f32_e32 v84, v123, v82
	v_add_f32_e32 v82, v122, v82
	v_add_f32_e32 v70, v112, v56
	v_add_f32_e32 v56, v111, v56
	v_add_f32_e32 v85, v121, v82
	v_add_f32_e32 v82, v120, v82
	v_add_f32_e32 v56, v110, v56
	v_add_f32_e32 v71, v125, v126
	v_add_f32_e32 v82, v119, v82
	v_mul_f32_e32 v68, 0x3fb8aa3b, v68
	v_mul_f32_e32 v69, 0x3fb8aa3b, v69
	v_mul_f32_e32 v70, 0x3fb8aa3b, v70
	v_mul_f32_e32 v56, 0x3fb8aa3b, v56
	v_mul_f32_e32 v71, 0x3fb8aa3b, v71
	v_mul_f32_e32 v84, 0x3fb8aa3b, v84
	v_mul_f32_e32 v85, 0x3fb8aa3b, v85
	v_mul_f32_e32 v82, 0x3fb8aa3b, v82
	v_exp_f32_e32 v68, v68
	v_exp_f32_e32 v69, v69
	v_exp_f32_e32 v70, v70
	v_exp_f32_e32 v56, v56
	v_exp_f32_e32 v71, v71
	v_exp_f32_e32 v84, v84
	v_exp_f32_e32 v85, v85
	v_exp_f32_e32 v82, v82
	v_cvt_pk_bf16_f32 v62, v60, v62
	v_cvt_pk_bf16_f32 v63, v64, v63
	v_cvt_pk_bf16_f32 v64, v58, v67
	v_cvt_pk_bf16_f32 v65, v66, v65
	v_cvt_pk_bf16_f32 v66, v56, v70
	v_cvt_pk_bf16_f32 v67, v69, v68
	v_mfma_f32_16x16x32_bf16 v[0:3], v[52:55], v[62:65], v[0:3]
	v_cvt_pk_bf16_f32 v68, v82, v85
	v_cvt_pk_bf16_f32 v69, v84, v71
	v_mfma_f32_16x16x32_bf16 v[4:7], v[44:47], v[62:65], v[4:7]
	v_mfma_f32_16x16x32_bf16 v[8:11], v[36:39], v[62:65], v[8:11]
	v_mfma_f32_16x16x32_bf16 v[12:15], v[28:31], v[62:65], v[12:15]
	v_mfma_f32_16x16x32_bf16 v[0:3], v[48:51], v[66:69], v[0:3]
	v_mfma_f32_16x16x32_bf16 v[4:7], v[40:43], v[66:69], v[4:7]
	v_mfma_f32_16x16x32_bf16 v[8:11], v[32:35], v[66:69], v[8:11]
	v_mfma_f32_16x16x32_bf16 v[12:15], v[24:27], v[66:69], v[12:15]
	s_cbranch_scc0 .Lcc_last
	v_add_f32_e32 v24, v93, v94
	v_add_f32_e32 v24, v24, v95
	v_add_f32_e32 v24, v24, v96
	v_add_f32_e32 v24, v24, v61
	v_add_f32_e32 v24, v24, v59
	v_add_f32_e32 v24, v24, v57
	v_add_f32_e32 v83, v83, v24
	v_cmp_lt_f32_e32 vcc, s38, v83
	s_cbranch_vccnz .Lcc_after

.LBB0_587:
	s_lshl_b64 s[6:7], 1, s22
	s_and_b64 s[8:9], s[6:7], s[38:39]
	s_cmp_eq_u64 s[8:9], 0
	s_cbranch_scc1 .LBB0_597
	s_add_i32 s8, 0, 0x4000
	s_cmp_eq_u32 s45, 0
	s_cselect_b32 s8, s8, s91
	v_add3_u32 v64, s8, v148, v150
	ds_read_b128 v[24:27], v64
	ds_read_b128 v[28:31], v64 offset:64
	ds_read_b128 v[32:35], v64 offset:2560
	ds_read_b128 v[36:39], v64 offset:2624
	s_cselect_b32 s8, s77, s46
	s_cmp_eq_u32 s22, 0
	s_waitcnt lgkmcnt(3)
	v_mfma_f32_16x16x32_bf16 v[24:27], v[24:27], v[20:23], 0
	s_waitcnt lgkmcnt(1)
	v_mfma_f32_16x16x32_bf16 v[32:35], v[32:35], v[20:23], 0
	v_mfma_f32_16x16x32_bf16 v[108:111], v[28:31], v[0:3], v[24:27]
	s_nop 5
	ds_read_b128 v[24:27], v64 offset:5120
	ds_read_b128 v[28:31], v64 offset:5184
	s_waitcnt lgkmcnt(2)
	v_mfma_f32_16x16x32_bf16 v[104:107], v[36:39], v[0:3], v[32:35]
	s_nop 2
	ds_read_b128 v[32:35], v64 offset:7680
	ds_read_b128 v[36:39], v64 offset:7744
	v_add3_u32 v64, s8, v149, v148
	ds_read_b128 v[92:95], v64
	ds_read_b128 v[88:91], v64 offset:64
	s_waitcnt lgkmcnt(5)
	v_mfma_f32_16x16x32_bf16 v[24:27], v[24:27], v[20:23], 0
	ds_read_b128 v[84:87], v64 offset:2560
	ds_read_b128 v[80:83], v64 offset:2624
	ds_read_b128 v[76:79], v64 offset:5120
	ds_read_b128 v[72:75], v64 offset:5184
	ds_read_b128 v[68:71], v64 offset:7680
	ds_read_b128 v[64:67], v64 offset:7744
	s_cselect_b64 s[8:9], -1, 0
	s_waitcnt lgkmcnt(10)
	v_mfma_f32_16x16x32_bf16 v[100:103], v[28:31], v[0:3], v[24:27]
	s_and_b64 vcc, exec, s[8:9]
	s_waitcnt lgkmcnt(9)
	v_mfma_f32_16x16x32_bf16 v[24:27], v[32:35], v[20:23], 0
	s_waitcnt lgkmcnt(8)
	v_mfma_f32_16x16x32_bf16 v[96:99], v[36:39], v[0:3], v[24:27]
	s_cbranch_vccnz .LBB0_591
	s_lshl_b32 s8, s22, 6
	s_or_b32 s8, s8, 63
	s_cmp_le_i32 s8, s56
	s_mov_b64 s[8:9], -1
	s_cbranch_scc0 .LBB0_592
	s_nop 0
	v_and_b32_e32 v25, s7, v115
	v_and_b32_e32 v24, s6, v134
	v_cmp_eq_u64_e32 vcc, 0, v[24:25]
	s_mov_b64 s[8:9], 0
	s_nop 0
	v_cndmask_b32_e32 v24, 0, v241, vcc
	v_max3_f32 v27, v108, v109, v110
	v_max3_f32 v27, v27, v111, v104
	v_max3_f32 v27, v27, v105, v106
	v_max3_f32 v27, v27, v107, v100
	v_max3_f32 v27, v27, v101, v102
	v_max3_f32 v27, v27, v103, v96
	v_max3_f32 v27, v27, v97, v98
	v_max_f32_e32 v27, v27, v99
	v_mov_b32_e32 v127, v27
	s_nop 1
	v_permlane16_swap_b32_e32 v27, v127
	v_max_f32_e32 v27, v27, v127
	v_mov_b32_e32 v127, v27
	s_nop 1
	v_permlane32_swap_b32_e32 v27, v127
	v_max_f32_e32 v27, v27, v127
	v_fmamk_f32 v27, v27, 0x3e38aa3b, v24
	v_max3_f32 v127, v125, v27, s71
	v_sub_f32_e32 v27, v125, v127
	v_sub_f32_e32 v24, v24, v127
	v_exp_f32_e32 v142, v27
	v_fmamk_f32 v25, v108, 0x3e38aa3b, v24
	v_exp_f32_e32 v25, v25
	v_fmamk_f32 v26, v109, 0x3e38aa3b, v24
	v_exp_f32_e32 v26, v26
	v_fmamk_f32 v28, v110, 0x3e38aa3b, v24
	v_exp_f32_e32 v28, v28
	v_add_f32_e32 v138, 0, v25
	v_fmamk_f32 v29, v111, 0x3e38aa3b, v24
	v_exp_f32_e32 v29, v29
	v_add_f32_e32 v138, v26, v138
	v_fmamk_f32 v30, v104, 0x3e38aa3b, v24
	v_exp_f32_e32 v30, v30
	v_add_f32_e32 v138, v28, v138
	v_fmamk_f32 v31, v105, 0x3e38aa3b, v24
	v_exp_f32_e32 v31, v31
	v_add_f32_e32 v138, v29, v138
	v_fmamk_f32 v32, v106, 0x3e38aa3b, v24
	v_exp_f32_e32 v32, v32
	v_add_f32_e32 v138, v30, v138
	v_fmamk_f32 v33, v107, 0x3e38aa3b, v24
	v_exp_f32_e32 v33, v33
	v_add_f32_e32 v138, v31, v138
	v_fmamk_f32 v34, v100, 0x3e38aa3b, v24
	v_exp_f32_e32 v34, v34
	v_add_f32_e32 v138, v32, v138
	v_fmamk_f32 v35, v101, 0x3e38aa3b, v24
	v_exp_f32_e32 v35, v35
	v_add_f32_e32 v138, v33, v138
	v_fmamk_f32 v139, v102, 0x3e38aa3b, v24
	v_exp_f32_e32 v139, v139
	v_add_f32_e32 v138, v34, v138
	v_fmamk_f32 v140, v103, 0x3e38aa3b, v24
	v_exp_f32_e32 v140, v140
	v_add_f32_e32 v138, v35, v138
	v_fmamk_f32 v141, v96, 0x3e38aa3b, v24
	v_exp_f32_e32 v141, v141
	v_add_f32_e32 v36, v139, v138
	v_fmamk_f32 v143, v97, 0x3e38aa3b, v24
	v_exp_f32_e32 v143, v143
	v_add_f32_e32 v36, v140, v36
	v_fmamk_f32 v144, v98, 0x3e38aa3b, v24
	v_exp_f32_e32 v144, v144
	v_add_f32_e32 v36, v141, v36
	v_fmamk_f32 v24, v99, 0x3e38aa3b, v24
	v_exp_f32_e32 v24, v24
	v_add_f32_e32 v36, v143, v36
	v_add_f32_e32 v36, v144, v36
	v_add_f32_e32 v131, v24, v36
	v_fmac_f32_e32 v131, v121, v142
	v_cvt_pk_bf16_f32 v36, v25, v26
	v_cvt_pk_bf16_f32 v37, v28, v29
	v_cvt_pk_bf16_f32 v38, v30, v31
	v_cvt_pk_bf16_f32 v39, v32, v33
	v_cvt_pk_bf16_f32 v138, v34, v35
	v_cvt_pk_bf16_f32 v139, v139, v140
	v_cvt_pk_bf16_f32 v140, v141, v143
	v_cvt_pk_bf16_f32 v141, v144, v24
	v_pk_mul_f32 v[26:27], v[62:63], v[142:143] op_sel_hi:[1,0]
	v_pk_mul_f32 v[24:25], v[60:61], v[142:143] op_sel_hi:[1,0]
	v_pk_mul_f32 v[30:31], v[58:59], v[142:143] op_sel_hi:[1,0]
	v_pk_mul_f32 v[28:29], v[56:57], v[142:143] op_sel_hi:[1,0]
	v_pk_mul_f32 v[34:35], v[54:55], v[142:143] op_sel_hi:[1,0]
	v_pk_mul_f32 v[32:33], v[52:53], v[142:143] op_sel_hi:[1,0]
	v_pk_mul_f32 v[144:145], v[50:51], v[142:143] op_sel_hi:[1,0]
	v_pk_mul_f32 v[142:143], v[48:49], v[142:143] op_sel_hi:[1,0]
	s_waitcnt lgkmcnt(0)
	v_mfma_f32_16x16x32_bf16 v[24:27], v[92:95], v[36:39], v[24:27]
	v_mfma_f32_16x16x32_bf16 v[28:31], v[84:87], v[36:39], v[28:31]
	v_mfma_f32_16x16x32_bf16 v[32:35], v[76:79], v[36:39], v[32:35]
	v_mfma_f32_16x16x32_bf16 v[36:39], v[68:71], v[36:39], v[142:145]
	v_mfma_f32_16x16x32_bf16 v[24:27], v[88:91], v[138:141], v[24:27]
	v_mfma_f32_16x16x32_bf16 v[28:31], v[80:83], v[138:141], v[28:31]
	v_mfma_f32_16x16x32_bf16 v[32:35], v[72:75], v[138:141], v[32:35]
	v_mfma_f32_16x16x32_bf16 v[36:39], v[64:67], v[138:141], v[36:39]
	s_branch .LBB0_592

.LBB0_607:
	s_add_i32 s57, 0, 0x4000
	s_cmp_eq_u32 s55, 0
	s_cselect_b64 s[52:53], -1, 0
	s_and_b64 s[6:7], s[52:53], exec
	s_cselect_b32 s6, s57, s91
	v_add3_u32 v72, s6, v148, v150
	ds_read_b128 v[48:51], v72
	ds_read_b128 v[52:55], v72 offset:64
	ds_read_b128 v[56:59], v72 offset:2560
	ds_read_b128 v[60:63], v72 offset:2624
	ds_read_b128 v[64:67], v72 offset:5120
	ds_read_b128 v[68:71], v72 offset:5184
	s_cselect_b32 s6, s77, s46
	s_waitcnt lgkmcnt(5)
	v_mfma_f32_16x16x32_bf16 v[48:51], v[48:51], v[20:23], 0
	v_add3_u32 v92, s6, v149, v148
	s_cmp_lt_i32 s92, s54
	s_cselect_b64 s[6:7], -1, 0
	s_waitcnt lgkmcnt(4)
	v_mfma_f32_16x16x32_bf16 v[100:103], v[52:55], v[0:3], v[48:51]
	ds_read_b128 v[80:83], v72 offset:7744
	s_add_i32 s8, s92, 63
	s_cmp_gt_i32 s8, s56
	s_nop 0
	ds_read_b128 v[48:51], v72 offset:7680
	s_waitcnt lgkmcnt(5)
	v_mfma_f32_16x16x32_bf16 v[56:59], v[56:59], v[20:23], 0
	s_cselect_b64 s[8:9], -1, 0
	s_or_b64 s[6:7], s[6:7], s[8:9]
	s_andn2_b64 vcc, exec, s[6:7]
	s_waitcnt lgkmcnt(3)
	v_mfma_f32_16x16x32_bf16 v[64:67], v[64:67], v[20:23], 0
	s_mov_b64 s[6:7], -1
	s_waitcnt lgkmcnt(0)
	v_mfma_f32_16x16x32_bf16 v[84:87], v[48:51], v[20:23], 0
	v_mfma_f32_16x16x32_bf16 v[96:99], v[60:63], v[0:3], v[56:59]
	v_mfma_f32_16x16x32_bf16 v[88:91], v[68:71], v[0:3], v[64:67]
	ds_read_b128 v[76:79], v92
	ds_read_b128 v[72:75], v92 offset:64
	ds_read_b128 v[68:71], v92 offset:2560
	ds_read_b128 v[64:67], v92 offset:2624
	ds_read_b128 v[60:63], v92 offset:5120
	ds_read_b128 v[56:59], v92 offset:5184
	ds_read_b128 v[52:55], v92 offset:7680
	ds_read_b128 v[48:51], v92 offset:7744
	v_mfma_f32_16x16x32_bf16 v[84:87], v[80:83], v[0:3], v[84:87]
	s_cbranch_vccnz .LBB0_613
	s_andn2_b64 vcc, exec, s[6:7]
	s_cbranch_vccz .LBB0_614
